# attention finalize: exchange reads batched (16+ in flight, fresh temp regs), row loop processes two rows with interleaved independent chains; softmax stream reordered; padded bias table; fall-through
# speedup vs baseline: 1.0080x; 1.0080x over previous
; DI void phase_attn(int wid0, const Params& p, int L, unsigned char* lds, bool dry) {
;     ...
;                 float pmax = p0[0];
; #pragma unroll
;                 for (int r = 1; r < 16; ++r) pmax = fmaxf(pmax, p0[r]);
;                 { auto rr = __builtin_amdgcn_permlane32_swap(__float_as_uint(pmax), __float_as_uint(pmax), false, false); pmax = fmaxf(__uint_as_float(rr[0]), __uint_as_float(rr[1])); }
;                 float mn, alpha;
;                 if (__all(pmax - m_reg <= ATT_THR2)) { mn = m_reg; alpha = 1.f; }
;                 else { mn = fmaxf(m_reg, pmax); alpha = __builtin_amdgcn_exp2f(m_reg - mn); m_reg = mn; }
;                 float ps = 0.f;
; #pragma unroll
;                 for (int r = 0; r < 16; ++r) { p0[r] = __builtin_amdgcn_exp2f(p0[r] - mn); ps += p0[r]; }
;                 { auto rr = __builtin_amdgcn_permlane32_swap(__float_as_uint(ps), __float_as_uint(ps), false, false); ps = __uint_as_float(rr[0]) + __uint_as_float(rr[1]); }
;                 l_reg = l_reg * alpha + ps;
;                 __builtin_amdgcn_sched_barrier(0);
;                 bf16x8 pa0, pa1;
;     ...
;                 PK4(p0, 0, pa0); PK4(p0, 8, pa1);
.Lattn_region0:
	ds_read_b64_tr_b16 v[216:217], v212 offset:49152
	ds_read_b64_tr_b16 v[218:219], v212 offset:53248
	ds_read_b64_tr_b16 v[220:221], v212 offset:57344
	ds_read_b64_tr_b16 v[222:223], v212 offset:61440
	ds_read_b64_tr_b16 v[236:237], v212 offset:49664
	ds_read_b64_tr_b16 v[238:239], v212 offset:53760
	ds_read_b64_tr_b16 v[240:241], v212 offset:57856
	ds_read_b64_tr_b16 v[242:243], v212 offset:61952
	v_max3_f32 v226, v140, v141, v142
	v_max3_f32 v227, v148, v149, v150
	v_max3_f32 v226, v226, v143, v144
	v_max3_f32 v227, v227, v151, v152
	v_max3_f32 v226, v226, v145, v146
	v_max3_f32 v227, v227, v153, v154
	v_max3_f32 v226, v226, v147, v155
	v_max_f32_e32 v226, v226, v227
	v_mov_b32_e32 v227, v226
	s_nop 1
	v_permlane32_swap_b32_e32 v226, v227
	v_max_f32_e32 v226, v226, v227
	v_fma_f32 v226, v226, s82, v231
	v_sub_f32_e32 v227, v226, v213
	v_cmp_ge_f32_e32 vcc, s97, v227
	s_cmp_eq_u64 vcc, exec
	v_max_f32_e32 v226, v213, v226
	s_cselect_b64 vcc, -1, 0
	v_sub_f32_e32 v227, v213, v226
	v_cndmask_b32_e32 v213, v226, v213, vcc
	v_sub_f32_e32 v230, v231, v213
	s_waitcnt lgkmcnt(4)
	v_mfma_f32_32x32x16_bf16 v[114:129], v[132:135], v[216:219], v[114:129]
	v_mfma_f32_32x32x16_bf16 v[114:129], v[136:139], v[220:223], v[114:129]
	v_fma_f32 v140, v140, s82, v230
	v_fma_f32 v141, v141, s82, v230
	v_exp_f32_e32 v140, v140
	v_fma_f32 v142, v142, s82, v230
	v_exp_f32_e32 v141, v141
	ds_read_b64_tr_b16 v[216:217], v212 offset:50176
	ds_read_b64_tr_b16 v[218:219], v212 offset:54272
	ds_read_b64_tr_b16 v[220:221], v212 offset:58368
	ds_read_b64_tr_b16 v[222:223], v212 offset:62464
	s_waitcnt lgkmcnt(4)
	v_mfma_f32_32x32x16_bf16 v[98:113], v[132:135], v[236:239], v[98:113]
	v_fma_f32 v143, v143, s82, v230
	v_exp_f32_e32 v142, v142
	v_add_f32_e32 v226, v140, v141
	v_fma_f32 v144, v144, s82, v230
	v_exp_f32_e32 v143, v143
	v_mfma_f32_32x32x16_bf16 v[98:113], v[136:139], v[240:243], v[98:113]
	v_add_f32_e32 v226, v226, v142
	v_fma_f32 v145, v145, s82, v230
	v_exp_f32_e32 v144, v144
	v_add_f32_e32 v226, v226, v143
	v_fma_f32 v146, v146, s82, v230
	ds_read_b64_tr_b16 v[236:237], v212 offset:50688
	ds_read_b64_tr_b16 v[238:239], v212 offset:54784
	ds_read_b64_tr_b16 v[240:241], v212 offset:58880
	ds_read_b64_tr_b16 v[242:243], v212 offset:62976
	s_waitcnt lgkmcnt(4)
	v_mfma_f32_32x32x16_bf16 v[82:97], v[132:135], v[216:219], v[82:97]
	v_exp_f32_e32 v145, v145
	v_add_f32_e32 v226, v226, v144
	v_fma_f32 v147, v147, s82, v230
	v_exp_f32_e32 v146, v146
	v_mfma_f32_32x32x16_bf16 v[82:97], v[136:139], v[220:223], v[82:97]
	v_add_f32_e32 v226, v226, v145
	v_fma_f32 v148, v148, s82, v230
	v_exp_f32_e32 v147, v147
	v_add_f32_e32 v226, v226, v146
	v_fma_f32 v149, v149, s82, v230
	ds_read_b64_tr_b16 v[216:217], v212 offset:51200
	ds_read_b64_tr_b16 v[218:219], v212 offset:55296
	ds_read_b64_tr_b16 v[220:221], v212 offset:59392
	ds_read_b64_tr_b16 v[222:223], v212 offset:63488
	s_waitcnt lgkmcnt(4)
	v_mfma_f32_32x32x16_bf16 v[66:81], v[132:135], v[236:239], v[66:81]
	v_exp_f32_e32 v148, v148
	v_add_f32_e32 v226, v226, v147
	v_fma_f32 v150, v150, s82, v230
	v_exp_f32_e32 v149, v149
	v_mfma_f32_32x32x16_bf16 v[66:81], v[136:139], v[240:243], v[66:81]
	v_add_f32_e32 v226, v226, v148
	v_fma_f32 v151, v151, s82, v230
	v_exp_f32_e32 v150, v150
	v_add_f32_e32 v226, v226, v149
	ds_read_b64_tr_b16 v[236:237], v212 offset:51712
	ds_read_b64_tr_b16 v[238:239], v212 offset:55808
	ds_read_b64_tr_b16 v[240:241], v212 offset:59904
	ds_read_b64_tr_b16 v[242:243], v212 offset:64000
	s_waitcnt lgkmcnt(4)
	v_mfma_f32_32x32x16_bf16 v[50:65], v[132:135], v[216:219], v[50:65]
	v_fma_f32 v152, v152, s82, v230
	v_exp_f32_e32 v151, v151
	v_add_f32_e32 v226, v226, v150
	v_fma_f32 v153, v153, s82, v230
	v_mfma_f32_32x32x16_bf16 v[50:65], v[136:139], v[220:223], v[50:65]
	v_exp_f32_e32 v152, v152
	v_add_f32_e32 v226, v226, v151
	v_fma_f32 v154, v154, s82, v230
	v_exp_f32_e32 v153, v153
	ds_read_b64_tr_b16 v[216:217], v212 offset:52224
	ds_read_b64_tr_b16 v[218:219], v212 offset:56320
	ds_read_b64_tr_b16 v[220:221], v212 offset:60416
	ds_read_b64_tr_b16 v[222:223], v212 offset:64512
	s_waitcnt lgkmcnt(4)
	v_mfma_f32_32x32x16_bf16 v[34:49], v[132:135], v[236:239], v[34:49]
	v_add_f32_e32 v226, v226, v152
	v_fma_f32 v155, v155, s82, v230
	v_exp_f32_e32 v154, v154
	v_add_f32_e32 v226, v226, v153
	v_mfma_f32_32x32x16_bf16 v[34:49], v[136:139], v[240:243], v[34:49]
	v_exp_f32_e32 v155, v155
	v_add_f32_e32 v226, v226, v154
	v_exp_f32_e32 v227, v227
	ds_read_b64_tr_b16 v[236:237], v212 offset:52736
	ds_read_b64_tr_b16 v[238:239], v212 offset:56832
	ds_read_b64_tr_b16 v[240:241], v212 offset:60928
	ds_read_b64_tr_b16 v[242:243], v212 offset:65024
	s_waitcnt lgkmcnt(4)
	v_mfma_f32_32x32x16_bf16 v[18:33], v[132:135], v[216:219], v[18:33]
	v_add_f32_e32 v228, v226, v155
	v_cndmask_b32_e64 v227, v227, 1.0, vcc
	v_mov_b32_e32 v229, v228
	v_cvt_pk_bf16_f32 v156, v140, v141
	v_cvt_pk_bf16_f32 v157, v142, v143
	v_mfma_f32_32x32x16_bf16 v[18:33], v[136:139], v[220:223], v[18:33]
	v_cvt_pk_bf16_f32 v158, v144, v145
	v_cvt_pk_bf16_f32 v159, v146, v147
	v_cvt_pk_bf16_f32 v160, v148, v149
	v_cvt_pk_bf16_f32 v161, v150, v151
	v_cvt_pk_bf16_f32 v162, v152, v153
	s_waitcnt lgkmcnt(0)
	v_mfma_f32_32x32x16_bf16 v[2:17], v[132:135], v[236:239], v[2:17]
	v_cvt_pk_bf16_f32 v163, v154, v155
	v_permlane32_swap_b32_e32 v228, v229
	v_permlane32_swap_b32_e32 v156, v158
	v_permlane32_swap_b32_e32 v157, v159
	v_mfma_f32_32x32x16_bf16 v[2:17], v[136:139], v[240:243], v[2:17]
	v_permlane32_swap_b32_e32 v160, v162
	v_permlane32_swap_b32_e32 v161, v163
	v_add_f32_e32 v228, v228, v229
	v_fma_f32 v130, v130, v227, v228
	s_cbranch_vccz .Lattn_rescale0

; DI void phase_attn(int wid0, const Params& p, int L, unsigned char* lds, bool dry) {
;     ...
;                 float pmax = p0[0];
; #pragma unroll
;                 for (int r = 1; r < 16; ++r) pmax = fmaxf(pmax, p0[r]);
;                 { auto rr = __builtin_amdgcn_permlane32_swap(__float_as_uint(pmax), __float_as_uint(pmax), false, false); pmax = fmaxf(__uint_as_float(rr[0]), __uint_as_float(rr[1])); }
;                 float mn, alpha;
;                 if (__all(pmax - m_reg <= ATT_THR2)) { mn = m_reg; alpha = 1.f; }
;                 else { mn = fmaxf(m_reg, pmax); alpha = __builtin_amdgcn_exp2f(m_reg - mn); m_reg = mn; }
;                 float ps = 0.f;
; #pragma unroll
;                 for (int r = 0; r < 16; ++r) { p0[r] = __builtin_amdgcn_exp2f(p0[r] - mn); ps += p0[r]; }
;                 { auto rr = __builtin_amdgcn_permlane32_swap(__float_as_uint(ps), __float_as_uint(ps), false, false); ps = __uint_as_float(rr[0]) + __uint_as_float(rr[1]); }
;                 l_reg = l_reg * alpha + ps;
;                 __builtin_amdgcn_sched_barrier(0);
;                 bf16x8 pa0, pa1;
;     ...
;                 PK4(p0, 0, pa0); PK4(p0, 8, pa1);
.Lattn_region1:
	ds_read_b64_tr_b16 v[216:217], v212 offset:0
	ds_read_b64_tr_b16 v[218:219], v212 offset:4096
	ds_read_b64_tr_b16 v[220:221], v212 offset:8192
	ds_read_b64_tr_b16 v[222:223], v212 offset:12288
	ds_read_b64_tr_b16 v[236:237], v212 offset:512
	ds_read_b64_tr_b16 v[238:239], v212 offset:4608
	ds_read_b64_tr_b16 v[240:241], v212 offset:8704
	ds_read_b64_tr_b16 v[242:243], v212 offset:12800
	v_max3_f32 v226, v140, v141, v142
	v_max3_f32 v227, v148, v149, v150
	v_max3_f32 v226, v226, v143, v144
	v_max3_f32 v227, v227, v151, v152
	v_max3_f32 v226, v226, v145, v146
	v_max3_f32 v227, v227, v153, v154
	v_max3_f32 v226, v226, v147, v155
	v_max_f32_e32 v226, v226, v227
	v_mov_b32_e32 v227, v226
	s_nop 1
	v_permlane32_swap_b32_e32 v226, v227
	v_max_f32_e32 v226, v226, v227
	v_fma_f32 v226, v226, s82, v231
	v_sub_f32_e32 v227, v226, v213
	v_cmp_ge_f32_e32 vcc, s97, v227
	s_cmp_eq_u64 vcc, exec
	v_max_f32_e32 v226, v213, v226
	s_cselect_b64 vcc, -1, 0
	v_sub_f32_e32 v227, v213, v226
	v_cndmask_b32_e32 v213, v226, v213, vcc
	v_sub_f32_e32 v230, v231, v213
	s_waitcnt lgkmcnt(4)
	v_mfma_f32_32x32x16_bf16 v[114:129], v[156:159], v[216:219], v[114:129]
	v_mfma_f32_32x32x16_bf16 v[114:129], v[160:163], v[220:223], v[114:129]
	v_fma_f32 v140, v140, s82, v230
	v_fma_f32 v141, v141, s82, v230
	v_exp_f32_e32 v140, v140
	v_fma_f32 v142, v142, s82, v230
	v_exp_f32_e32 v141, v141
	ds_read_b64_tr_b16 v[216:217], v212 offset:1024
	ds_read_b64_tr_b16 v[218:219], v212 offset:5120
	ds_read_b64_tr_b16 v[220:221], v212 offset:9216
	ds_read_b64_tr_b16 v[222:223], v212 offset:13312
	s_waitcnt lgkmcnt(4)
	v_mfma_f32_32x32x16_bf16 v[98:113], v[156:159], v[236:239], v[98:113]
	v_fma_f32 v143, v143, s82, v230
	v_exp_f32_e32 v142, v142
	v_add_f32_e32 v226, v140, v141
	v_fma_f32 v144, v144, s82, v230
	v_exp_f32_e32 v143, v143
	v_mfma_f32_32x32x16_bf16 v[98:113], v[160:163], v[240:243], v[98:113]
	v_add_f32_e32 v226, v226, v142
	v_fma_f32 v145, v145, s82, v230
	v_exp_f32_e32 v144, v144
	v_add_f32_e32 v226, v226, v143
	v_fma_f32 v146, v146, s82, v230
	ds_read_b64_tr_b16 v[236:237], v212 offset:1536
	ds_read_b64_tr_b16 v[238:239], v212 offset:5632
	ds_read_b64_tr_b16 v[240:241], v212 offset:9728
	ds_read_b64_tr_b16 v[242:243], v212 offset:13824
	s_waitcnt lgkmcnt(4)
	v_mfma_f32_32x32x16_bf16 v[82:97], v[156:159], v[216:219], v[82:97]
	v_exp_f32_e32 v145, v145
	v_add_f32_e32 v226, v226, v144
	v_fma_f32 v147, v147, s82, v230
	v_exp_f32_e32 v146, v146
	v_mfma_f32_32x32x16_bf16 v[82:97], v[160:163], v[220:223], v[82:97]
	v_add_f32_e32 v226, v226, v145
	v_fma_f32 v148, v148, s82, v230
	v_exp_f32_e32 v147, v147
	v_add_f32_e32 v226, v226, v146
	v_fma_f32 v149, v149, s82, v230
	ds_read_b64_tr_b16 v[216:217], v212 offset:2048
	ds_read_b64_tr_b16 v[218:219], v212 offset:6144
	ds_read_b64_tr_b16 v[220:221], v212 offset:10240
	ds_read_b64_tr_b16 v[222:223], v212 offset:14336
	s_waitcnt lgkmcnt(4)
	v_mfma_f32_32x32x16_bf16 v[66:81], v[156:159], v[236:239], v[66:81]
	v_exp_f32_e32 v148, v148
	v_add_f32_e32 v226, v226, v147
	v_fma_f32 v150, v150, s82, v230
	v_exp_f32_e32 v149, v149
	v_mfma_f32_32x32x16_bf16 v[66:81], v[160:163], v[240:243], v[66:81]
	v_add_f32_e32 v226, v226, v148
	v_fma_f32 v151, v151, s82, v230
	v_exp_f32_e32 v150, v150
	v_add_f32_e32 v226, v226, v149
	ds_read_b64_tr_b16 v[236:237], v212 offset:2560
	ds_read_b64_tr_b16 v[238:239], v212 offset:6656
	ds_read_b64_tr_b16 v[240:241], v212 offset:10752
	ds_read_b64_tr_b16 v[242:243], v212 offset:14848
	s_waitcnt lgkmcnt(4)
	v_mfma_f32_32x32x16_bf16 v[50:65], v[156:159], v[216:219], v[50:65]
	v_fma_f32 v152, v152, s82, v230
	v_exp_f32_e32 v151, v151
	v_add_f32_e32 v226, v226, v150
	v_fma_f32 v153, v153, s82, v230
	v_mfma_f32_32x32x16_bf16 v[50:65], v[160:163], v[220:223], v[50:65]
	v_exp_f32_e32 v152, v152
	v_add_f32_e32 v226, v226, v151
	v_fma_f32 v154, v154, s82, v230
	v_exp_f32_e32 v153, v153
	ds_read_b64_tr_b16 v[216:217], v212 offset:3072
	ds_read_b64_tr_b16 v[218:219], v212 offset:7168
	ds_read_b64_tr_b16 v[220:221], v212 offset:11264
	ds_read_b64_tr_b16 v[222:223], v212 offset:15360
	s_waitcnt lgkmcnt(4)
	v_mfma_f32_32x32x16_bf16 v[34:49], v[156:159], v[236:239], v[34:49]
	v_add_f32_e32 v226, v226, v152
	v_fma_f32 v155, v155, s82, v230
	v_exp_f32_e32 v154, v154
	v_add_f32_e32 v226, v226, v153
	v_mfma_f32_32x32x16_bf16 v[34:49], v[160:163], v[240:243], v[34:49]
	v_exp_f32_e32 v155, v155
	v_add_f32_e32 v226, v226, v154
	v_exp_f32_e32 v227, v227
	ds_read_b64_tr_b16 v[236:237], v212 offset:3584
	ds_read_b64_tr_b16 v[238:239], v212 offset:7680
	ds_read_b64_tr_b16 v[240:241], v212 offset:11776
	ds_read_b64_tr_b16 v[242:243], v212 offset:15872
	s_waitcnt lgkmcnt(4)
	v_mfma_f32_32x32x16_bf16 v[18:33], v[156:159], v[216:219], v[18:33]
	v_add_f32_e32 v228, v226, v155
	v_cndmask_b32_e64 v227, v227, 1.0, vcc
	v_mov_b32_e32 v229, v228
	v_cvt_pk_bf16_f32 v132, v140, v141
	v_cvt_pk_bf16_f32 v133, v142, v143
	v_mfma_f32_32x32x16_bf16 v[18:33], v[160:163], v[220:223], v[18:33]
	v_cvt_pk_bf16_f32 v134, v144, v145
	v_cvt_pk_bf16_f32 v135, v146, v147
	v_cvt_pk_bf16_f32 v136, v148, v149
	v_cvt_pk_bf16_f32 v137, v150, v151
	v_cvt_pk_bf16_f32 v138, v152, v153
	s_waitcnt lgkmcnt(0)
	v_mfma_f32_32x32x16_bf16 v[2:17], v[156:159], v[236:239], v[2:17]
	v_cvt_pk_bf16_f32 v139, v154, v155
	v_permlane32_swap_b32_e32 v228, v229
	v_permlane32_swap_b32_e32 v132, v134
	v_permlane32_swap_b32_e32 v133, v135
	v_mfma_f32_32x32x16_bf16 v[2:17], v[160:163], v[240:243], v[2:17]
	v_permlane32_swap_b32_e32 v136, v138
	v_permlane32_swap_b32_e32 v137, v139
	v_add_f32_e32 v228, v228, v229
	v_fma_f32 v130, v130, v227, v228
	s_cbranch_vccz .Lattn_rescale1

; DI void phase_attn(int wid0, const Params& p, int L, unsigned char* lds, bool dry) {
;     ...
;                 float pmax = p0[0];
; #pragma unroll
;                 for (int r = 1; r < 16; ++r) pmax = fmaxf(pmax, p0[r]);
;                 { auto rr = __builtin_amdgcn_permlane32_swap(__float_as_uint(pmax), __float_as_uint(pmax), false, false); pmax = fmaxf(__uint_as_float(rr[0]), __uint_as_float(rr[1])); }
;                 float mn, alpha;
;                 if (__all(pmax - m_reg <= ATT_THR2)) { mn = m_reg; alpha = 1.f; }
;                 else { mn = fmaxf(m_reg, pmax); alpha = __builtin_amdgcn_exp2f(m_reg - mn); m_reg = mn; }
;                 float ps = 0.f;
; #pragma unroll
;                 for (int r = 0; r < 16; ++r) { p0[r] = __builtin_amdgcn_exp2f(p0[r] - mn); ps += p0[r]; }
;                 { auto rr = __builtin_amdgcn_permlane32_swap(__float_as_uint(ps), __float_as_uint(ps), false, false); ps = __uint_as_float(rr[0]) + __uint_as_float(rr[1]); }
;                 l_reg = l_reg * alpha + ps;
;                 __builtin_amdgcn_sched_barrier(0);
;                 bf16x8 pa0, pa1;
;     ...
;                 PK4(p0, 0, pa0); PK4(p0, 8, pa1);
.Lattn_region2:
	ds_read_b64_tr_b16 v[216:217], v212 offset:16384
	ds_read_b64_tr_b16 v[218:219], v212 offset:20480
	ds_read_b64_tr_b16 v[220:221], v212 offset:24576
	ds_read_b64_tr_b16 v[222:223], v212 offset:28672
	ds_read_b64_tr_b16 v[236:237], v212 offset:16896
	ds_read_b64_tr_b16 v[238:239], v212 offset:20992
	ds_read_b64_tr_b16 v[240:241], v212 offset:25088
	ds_read_b64_tr_b16 v[242:243], v212 offset:29184
	v_max3_f32 v226, v140, v141, v142
	v_max3_f32 v227, v148, v149, v150
	v_max3_f32 v226, v226, v143, v144
	v_max3_f32 v227, v227, v151, v152
	v_max3_f32 v226, v226, v145, v146
	v_max3_f32 v227, v227, v153, v154
	v_max3_f32 v226, v226, v147, v155
	v_max_f32_e32 v226, v226, v227
	v_mov_b32_e32 v227, v226
	s_nop 1
	v_permlane32_swap_b32_e32 v226, v227
	v_max_f32_e32 v226, v226, v227
	v_fma_f32 v226, v226, s82, v231
	v_sub_f32_e32 v227, v226, v213
	v_cmp_ge_f32_e32 vcc, s97, v227
	s_cmp_eq_u64 vcc, exec
	v_max_f32_e32 v226, v213, v226
	s_cselect_b64 vcc, -1, 0
	v_sub_f32_e32 v227, v213, v226
	v_cndmask_b32_e32 v213, v226, v213, vcc
	v_sub_f32_e32 v230, v231, v213
	s_waitcnt lgkmcnt(4)
	v_mfma_f32_32x32x16_bf16 v[114:129], v[132:135], v[216:219], v[114:129]
	v_mfma_f32_32x32x16_bf16 v[114:129], v[136:139], v[220:223], v[114:129]
	v_fma_f32 v140, v140, s82, v230
	v_fma_f32 v141, v141, s82, v230
	v_exp_f32_e32 v140, v140
	v_fma_f32 v142, v142, s82, v230
	v_exp_f32_e32 v141, v141
	ds_read_b64_tr_b16 v[216:217], v212 offset:17408
	ds_read_b64_tr_b16 v[218:219], v212 offset:21504
	ds_read_b64_tr_b16 v[220:221], v212 offset:25600
	ds_read_b64_tr_b16 v[222:223], v212 offset:29696
	s_waitcnt lgkmcnt(4)
	v_mfma_f32_32x32x16_bf16 v[98:113], v[132:135], v[236:239], v[98:113]
	v_fma_f32 v143, v143, s82, v230
	v_exp_f32_e32 v142, v142
	v_add_f32_e32 v226, v140, v141
	v_fma_f32 v144, v144, s82, v230
	v_exp_f32_e32 v143, v143
	v_mfma_f32_32x32x16_bf16 v[98:113], v[136:139], v[240:243], v[98:113]
	v_add_f32_e32 v226, v226, v142
	v_fma_f32 v145, v145, s82, v230
	v_exp_f32_e32 v144, v144
	v_add_f32_e32 v226, v226, v143
	v_fma_f32 v146, v146, s82, v230
	ds_read_b64_tr_b16 v[236:237], v212 offset:17920
	ds_read_b64_tr_b16 v[238:239], v212 offset:22016
	ds_read_b64_tr_b16 v[240:241], v212 offset:26112
	ds_read_b64_tr_b16 v[242:243], v212 offset:30208
	s_waitcnt lgkmcnt(4)
	v_mfma_f32_32x32x16_bf16 v[82:97], v[132:135], v[216:219], v[82:97]
	v_exp_f32_e32 v145, v145
	v_add_f32_e32 v226, v226, v144
	v_fma_f32 v147, v147, s82, v230
	v_exp_f32_e32 v146, v146
	v_mfma_f32_32x32x16_bf16 v[82:97], v[136:139], v[220:223], v[82:97]
	v_add_f32_e32 v226, v226, v145
	v_fma_f32 v148, v148, s82, v230
	v_exp_f32_e32 v147, v147
	v_add_f32_e32 v226, v226, v146
	v_fma_f32 v149, v149, s82, v230
	ds_read_b64_tr_b16 v[216:217], v212 offset:18432
	ds_read_b64_tr_b16 v[218:219], v212 offset:22528
	ds_read_b64_tr_b16 v[220:221], v212 offset:26624
	ds_read_b64_tr_b16 v[222:223], v212 offset:30720
	s_waitcnt lgkmcnt(4)
	v_mfma_f32_32x32x16_bf16 v[66:81], v[132:135], v[236:239], v[66:81]
	v_exp_f32_e32 v148, v148
	v_add_f32_e32 v226, v226, v147
	v_fma_f32 v150, v150, s82, v230
	v_exp_f32_e32 v149, v149
	v_mfma_f32_32x32x16_bf16 v[66:81], v[136:139], v[240:243], v[66:81]
	v_add_f32_e32 v226, v226, v148
	v_fma_f32 v151, v151, s82, v230
	v_exp_f32_e32 v150, v150
	v_add_f32_e32 v226, v226, v149
	ds_read_b64_tr_b16 v[236:237], v212 offset:18944
	ds_read_b64_tr_b16 v[238:239], v212 offset:23040
	ds_read_b64_tr_b16 v[240:241], v212 offset:27136
	ds_read_b64_tr_b16 v[242:243], v212 offset:31232
	s_waitcnt lgkmcnt(4)
	v_mfma_f32_32x32x16_bf16 v[50:65], v[132:135], v[216:219], v[50:65]
	v_fma_f32 v152, v152, s82, v230
	v_exp_f32_e32 v151, v151
	v_add_f32_e32 v226, v226, v150
	v_fma_f32 v153, v153, s82, v230
	v_mfma_f32_32x32x16_bf16 v[50:65], v[136:139], v[220:223], v[50:65]
	v_exp_f32_e32 v152, v152
	v_add_f32_e32 v226, v226, v151
	v_fma_f32 v154, v154, s82, v230
	v_exp_f32_e32 v153, v153
	ds_read_b64_tr_b16 v[216:217], v212 offset:19456
	ds_read_b64_tr_b16 v[218:219], v212 offset:23552
	ds_read_b64_tr_b16 v[220:221], v212 offset:27648
	ds_read_b64_tr_b16 v[222:223], v212 offset:31744
	s_waitcnt lgkmcnt(4)
	v_mfma_f32_32x32x16_bf16 v[34:49], v[132:135], v[236:239], v[34:49]
	v_add_f32_e32 v226, v226, v152
	v_fma_f32 v155, v155, s82, v230
	v_exp_f32_e32 v154, v154
	v_add_f32_e32 v226, v226, v153
	v_mfma_f32_32x32x16_bf16 v[34:49], v[136:139], v[240:243], v[34:49]
	v_exp_f32_e32 v155, v155
	v_add_f32_e32 v226, v226, v154
	v_exp_f32_e32 v227, v227
	ds_read_b64_tr_b16 v[236:237], v212 offset:19968
	ds_read_b64_tr_b16 v[238:239], v212 offset:24064
	ds_read_b64_tr_b16 v[240:241], v212 offset:28160
	ds_read_b64_tr_b16 v[242:243], v212 offset:32256
	s_waitcnt lgkmcnt(4)
	v_mfma_f32_32x32x16_bf16 v[18:33], v[132:135], v[216:219], v[18:33]
	v_add_f32_e32 v228, v226, v155
	v_cndmask_b32_e64 v227, v227, 1.0, vcc
	v_mov_b32_e32 v229, v228
	v_cvt_pk_bf16_f32 v156, v140, v141
	v_cvt_pk_bf16_f32 v157, v142, v143
	v_mfma_f32_32x32x16_bf16 v[18:33], v[136:139], v[220:223], v[18:33]
	v_cvt_pk_bf16_f32 v158, v144, v145
	v_cvt_pk_bf16_f32 v159, v146, v147
	v_cvt_pk_bf16_f32 v160, v148, v149
	v_cvt_pk_bf16_f32 v161, v150, v151
	v_cvt_pk_bf16_f32 v162, v152, v153
	s_waitcnt lgkmcnt(0)
	v_mfma_f32_32x32x16_bf16 v[2:17], v[132:135], v[236:239], v[2:17]
	v_cvt_pk_bf16_f32 v163, v154, v155
	v_permlane32_swap_b32_e32 v228, v229
	v_permlane32_swap_b32_e32 v156, v158
	v_permlane32_swap_b32_e32 v157, v159
	v_mfma_f32_32x32x16_bf16 v[2:17], v[136:139], v[240:243], v[2:17]
	v_permlane32_swap_b32_e32 v160, v162
	v_permlane32_swap_b32_e32 v161, v163
	v_add_f32_e32 v228, v228, v229
	v_fma_f32 v130, v130, v227, v228
	s_cbranch_vccz .Lattn_rescale2

; DI void phase_attn(int wid0, const Params& p, int L, unsigned char* lds, bool dry) {
;     ...
;                 float pmax = p0[0];
; #pragma unroll
;                 for (int r = 1; r < 16; ++r) pmax = fmaxf(pmax, p0[r]);
;                 { auto rr = __builtin_amdgcn_permlane32_swap(__float_as_uint(pmax), __float_as_uint(pmax), false, false); pmax = fmaxf(__uint_as_float(rr[0]), __uint_as_float(rr[1])); }
;                 float mn, alpha;
;                 if (__all(pmax - m_reg <= ATT_THR2)) { mn = m_reg; alpha = 1.f; }
;                 else { mn = fmaxf(m_reg, pmax); alpha = __builtin_amdgcn_exp2f(m_reg - mn); m_reg = mn; }
;                 float ps = 0.f;
; #pragma unroll
;                 for (int r = 0; r < 16; ++r) { p0[r] = __builtin_amdgcn_exp2f(p0[r] - mn); ps += p0[r]; }
;                 { auto rr = __builtin_amdgcn_permlane32_swap(__float_as_uint(ps), __float_as_uint(ps), false, false); ps = __uint_as_float(rr[0]) + __uint_as_float(rr[1]); }
;                 l_reg = l_reg * alpha + ps;
;                 __builtin_amdgcn_sched_barrier(0);
;                 bf16x8 pa0, pa1;
;     ...
;                 PK4(p0, 0, pa0); PK4(p0, 8, pa1);
.Lattn_region3:
	ds_read_b64_tr_b16 v[216:217], v212 offset:32768
	ds_read_b64_tr_b16 v[218:219], v212 offset:36864
	ds_read_b64_tr_b16 v[220:221], v212 offset:40960
	ds_read_b64_tr_b16 v[222:223], v212 offset:45056
	ds_read_b64_tr_b16 v[236:237], v212 offset:33280
	ds_read_b64_tr_b16 v[238:239], v212 offset:37376
	ds_read_b64_tr_b16 v[240:241], v212 offset:41472
	ds_read_b64_tr_b16 v[242:243], v212 offset:45568
	v_max3_f32 v226, v140, v141, v142
	v_max3_f32 v227, v148, v149, v150
	v_max3_f32 v226, v226, v143, v144
	v_max3_f32 v227, v227, v151, v152
	v_max3_f32 v226, v226, v145, v146
	v_max3_f32 v227, v227, v153, v154
	v_max3_f32 v226, v226, v147, v155
	v_max_f32_e32 v226, v226, v227
	v_mov_b32_e32 v227, v226
	s_nop 1
	v_permlane32_swap_b32_e32 v226, v227
	v_max_f32_e32 v226, v226, v227
	v_fma_f32 v226, v226, s82, v231
	v_sub_f32_e32 v227, v226, v213
	v_cmp_ge_f32_e32 vcc, s97, v227
	s_cmp_eq_u64 vcc, exec
	v_max_f32_e32 v226, v213, v226
	s_cselect_b64 vcc, -1, 0
	v_sub_f32_e32 v227, v213, v226
	v_cndmask_b32_e32 v213, v226, v213, vcc
	v_sub_f32_e32 v230, v231, v213
	s_waitcnt lgkmcnt(4)
	v_mfma_f32_32x32x16_bf16 v[114:129], v[156:159], v[216:219], v[114:129]
	v_mfma_f32_32x32x16_bf16 v[114:129], v[160:163], v[220:223], v[114:129]
	v_fma_f32 v140, v140, s82, v230
	v_fma_f32 v141, v141, s82, v230
	v_exp_f32_e32 v140, v140
	v_fma_f32 v142, v142, s82, v230
	v_exp_f32_e32 v141, v141
	ds_read_b64_tr_b16 v[216:217], v212 offset:33792
	ds_read_b64_tr_b16 v[218:219], v212 offset:37888
	ds_read_b64_tr_b16 v[220:221], v212 offset:41984
	ds_read_b64_tr_b16 v[222:223], v212 offset:46080
	s_waitcnt lgkmcnt(4)
	v_mfma_f32_32x32x16_bf16 v[98:113], v[156:159], v[236:239], v[98:113]
	v_fma_f32 v143, v143, s82, v230
	v_exp_f32_e32 v142, v142
	v_add_f32_e32 v226, v140, v141
	v_fma_f32 v144, v144, s82, v230
	v_exp_f32_e32 v143, v143
	v_mfma_f32_32x32x16_bf16 v[98:113], v[160:163], v[240:243], v[98:113]
	v_add_f32_e32 v226, v226, v142
	v_fma_f32 v145, v145, s82, v230
	v_exp_f32_e32 v144, v144
	v_add_f32_e32 v226, v226, v143
	v_fma_f32 v146, v146, s82, v230
	ds_read_b64_tr_b16 v[236:237], v212 offset:34304
	ds_read_b64_tr_b16 v[238:239], v212 offset:38400
	ds_read_b64_tr_b16 v[240:241], v212 offset:42496
	ds_read_b64_tr_b16 v[242:243], v212 offset:46592
	s_waitcnt lgkmcnt(4)
	v_mfma_f32_32x32x16_bf16 v[82:97], v[156:159], v[216:219], v[82:97]
	v_exp_f32_e32 v145, v145
	v_add_f32_e32 v226, v226, v144
	v_fma_f32 v147, v147, s82, v230
	v_exp_f32_e32 v146, v146
	v_mfma_f32_32x32x16_bf16 v[82:97], v[160:163], v[220:223], v[82:97]
	v_add_f32_e32 v226, v226, v145
	v_fma_f32 v148, v148, s82, v230
	v_exp_f32_e32 v147, v147
	v_add_f32_e32 v226, v226, v146
	v_fma_f32 v149, v149, s82, v230
	ds_read_b64_tr_b16 v[216:217], v212 offset:34816
	ds_read_b64_tr_b16 v[218:219], v212 offset:38912
	ds_read_b64_tr_b16 v[220:221], v212 offset:43008
	ds_read_b64_tr_b16 v[222:223], v212 offset:47104
	s_waitcnt lgkmcnt(4)
	v_mfma_f32_32x32x16_bf16 v[66:81], v[156:159], v[236:239], v[66:81]
	v_exp_f32_e32 v148, v148
	v_add_f32_e32 v226, v226, v147
	v_fma_f32 v150, v150, s82, v230
	v_exp_f32_e32 v149, v149
	v_mfma_f32_32x32x16_bf16 v[66:81], v[160:163], v[240:243], v[66:81]
	v_add_f32_e32 v226, v226, v148
	v_fma_f32 v151, v151, s82, v230
	v_exp_f32_e32 v150, v150
	v_add_f32_e32 v226, v226, v149
	ds_read_b64_tr_b16 v[236:237], v212 offset:35328
	ds_read_b64_tr_b16 v[238:239], v212 offset:39424
	ds_read_b64_tr_b16 v[240:241], v212 offset:43520
	ds_read_b64_tr_b16 v[242:243], v212 offset:47616
	s_waitcnt lgkmcnt(4)
	v_mfma_f32_32x32x16_bf16 v[50:65], v[156:159], v[216:219], v[50:65]
	v_fma_f32 v152, v152, s82, v230
	v_exp_f32_e32 v151, v151
	v_add_f32_e32 v226, v226, v150
	v_fma_f32 v153, v153, s82, v230
	v_mfma_f32_32x32x16_bf16 v[50:65], v[160:163], v[220:223], v[50:65]
	v_exp_f32_e32 v152, v152
	v_add_f32_e32 v226, v226, v151
	v_fma_f32 v154, v154, s82, v230
	v_exp_f32_e32 v153, v153
	ds_read_b64_tr_b16 v[216:217], v212 offset:35840
	ds_read_b64_tr_b16 v[218:219], v212 offset:39936
	ds_read_b64_tr_b16 v[220:221], v212 offset:44032
	ds_read_b64_tr_b16 v[222:223], v212 offset:48128
	s_waitcnt lgkmcnt(4)
	v_mfma_f32_32x32x16_bf16 v[34:49], v[156:159], v[236:239], v[34:49]
	v_add_f32_e32 v226, v226, v152
	v_fma_f32 v155, v155, s82, v230
	v_exp_f32_e32 v154, v154
	v_add_f32_e32 v226, v226, v153
	v_mfma_f32_32x32x16_bf16 v[34:49], v[160:163], v[240:243], v[34:49]
	v_exp_f32_e32 v155, v155
	v_add_f32_e32 v226, v226, v154
	v_exp_f32_e32 v227, v227
	ds_read_b64_tr_b16 v[236:237], v212 offset:36352
	ds_read_b64_tr_b16 v[238:239], v212 offset:40448
	ds_read_b64_tr_b16 v[240:241], v212 offset:44544
	ds_read_b64_tr_b16 v[242:243], v212 offset:48640
	s_waitcnt lgkmcnt(4)
	v_mfma_f32_32x32x16_bf16 v[18:33], v[156:159], v[216:219], v[18:33]
	v_add_f32_e32 v228, v226, v155
	v_cndmask_b32_e64 v227, v227, 1.0, vcc
	v_mov_b32_e32 v229, v228
	v_cvt_pk_bf16_f32 v132, v140, v141
	v_cvt_pk_bf16_f32 v133, v142, v143
	v_mfma_f32_32x32x16_bf16 v[18:33], v[160:163], v[220:223], v[18:33]
	v_cvt_pk_bf16_f32 v134, v144, v145
	v_cvt_pk_bf16_f32 v135, v146, v147
	v_cvt_pk_bf16_f32 v136, v148, v149
	v_cvt_pk_bf16_f32 v137, v150, v151
	v_cvt_pk_bf16_f32 v138, v152, v153
	s_waitcnt lgkmcnt(0)
	v_mfma_f32_32x32x16_bf16 v[2:17], v[156:159], v[236:239], v[2:17]
	v_cvt_pk_bf16_f32 v139, v154, v155
	v_permlane32_swap_b32_e32 v228, v229
	v_permlane32_swap_b32_e32 v132, v134
	v_permlane32_swap_b32_e32 v133, v135
	v_mfma_f32_32x32x16_bf16 v[2:17], v[160:163], v[240:243], v[2:17]
	v_permlane32_swap_b32_e32 v136, v138
	v_permlane32_swap_b32_e32 v137, v139
	v_add_f32_e32 v228, v228, v229
	v_fma_f32 v130, v130, v227, v228
	s_cbranch_vccz .Lattn_rescale3

; DI int crow(int r, int hi) { return (r & 3) + 8 * (r >> 2) + 4 * hi; }
; DI void finalize_attn(const Params& p, unsigned char* lds, f32x16 (&o)[8], float l_reg, int lane_k, int wid, bool meta, int qrow0, int hh, int di, float lambda_init, bool dry) {
;     ...
;     if (psub == 0) {
; #pragma unroll
;         for (int d = 0; d < 8; ++d)
; #pragma unroll
;             for (int r = 0; r < 16; ++r) o[d][r] += X[(rg * 128 + d * 16 + r) * 64 + lane];
;         asm volatile("s_waitcnt lgkmcnt(0)" ::: "memory");
;         float* R = (float*)(lds + rg * 32768);
; #pragma unroll
;         for (int d = 0; d < 8; ++d)
; #pragma unroll
;             for (int r = 0; r < 16; ++r) R[crow(r, hi) * 256 + 32 * d + r32] = o[d][r];
.LBB0_121:
	v_readlane_b32 s6, v244, 11
	v_readlane_b32 s7, v244, 12
	s_andn2_b64 vcc, exec, s[6:7]
	s_waitcnt lgkmcnt(0)
	s_barrier
	s_cbranch_vccnz .LBB0_77
	v_readlane_b32 s6, v244, 34
	s_nop 1
	v_lshl_add_u32 v48, v135, 2, s6
	ds_read2st64_b32 v[150:151], v48 offset1:1
	ds_read2st64_b32 v[152:153], v48 offset0:4 offset1:5
	ds_read2st64_b32 v[154:155], v48 offset0:10 offset1:11
	ds_read2st64_b32 v[156:157], v48 offset0:8 offset1:9
	ds_read2st64_b32 v[158:159], v48 offset0:2 offset1:3
	ds_read2st64_b32 v[160:161], v48 offset0:6 offset1:7
	ds_read2st64_b32 v[162:163], v48 offset0:30 offset1:31
	ds_read2st64_b32 v[164:165], v48 offset0:12 offset1:13
	ds_read2st64_b32 v[166:167], v48 offset0:32 offset1:33
	ds_read2st64_b32 v[168:169], v48 offset0:46 offset1:47
	ds_read2st64_b32 v[170:171], v48 offset0:48 offset1:49
	ds_read2st64_b32 v[172:173], v48 offset0:14 offset1:15
	ds_read2st64_b32 v[174:175], v48 offset0:34 offset1:35
	ds_read2st64_b32 v[200:201], v48 offset0:16 offset1:17
	ds_read2st64_b32 v[202:203], v48 offset0:36 offset1:37
	ds_read2st64_b32 v[204:205], v48 offset0:18 offset1:19
	ds_read2st64_b32 v[206:207], v48 offset0:38 offset1:39
	ds_read2st64_b32 v[216:217], v48 offset0:50 offset1:51
	ds_read2st64_b32 v[218:219], v48 offset0:20 offset1:21
	ds_read2st64_b32 v[220:221], v48 offset0:40 offset1:41
	ds_read2st64_b32 v[222:223], v48 offset0:22 offset1:23
	ds_read2st64_b32 v[232:233], v48 offset0:42 offset1:43
	ds_read2st64_b32 v[234:235], v48 offset0:24 offset1:25
	ds_read2st64_b32 v[236:237], v48 offset0:44 offset1:45
	ds_read2st64_b32 v[238:239], v48 offset0:52 offset1:53
	ds_read2st64_b32 v[240:241], v48 offset0:26 offset1:27
	ds_read2st64_b32 v[242:243], v48 offset0:54 offset1:55
	ds_read2st64_b32 v[248:249], v48 offset0:28 offset1:29
	ds_read2st64_b32 v[250:251], v48 offset0:56 offset1:57
	ds_read2st64_b32 v[252:253], v48 offset0:58 offset1:59
	ds_read2st64_b32 v[254:255], v48 offset0:60 offset1:61
	ds_read2st64_b32 v[226:227], v48 offset0:62 offset1:63
	s_waitcnt lgkmcnt(15)
	v_add_f32_e32 v17, v136, v150
	v_add_f32_e32 v16, v137, v151
	ds_read2st64_b32 v[150:151], v48 offset0:64 offset1:65
	v_add_f32_e32 v47, v118, v152
	v_add_f32_e32 v31, v140, v159
	v_add_f32_e32 v33, v119, v153
	ds_read2st64_b32 v[152:153], v48 offset0:66 offset1:67
	v_add_f32_e32 v32, v138, v158
	v_add_f32_e32 v63, v120, v160
	v_add_f32_e32 v49, v121, v161
	v_add_f32_e32 v65, v122, v156
	v_add_f32_e32 v64, v123, v157
	v_add_f32_e32 v81, v124, v154
	v_add_f32_e32 v80, v125, v155
	ds_read2st64_b32 v[154:155], v48 offset0:68 offset1:69
	ds_read2st64_b32 v[156:157], v48 offset0:70 offset1:71
	ds_read2st64_b32 v[158:159], v48 offset0:72 offset1:73
	ds_read2st64_b32 v[160:161], v48 offset0:74 offset1:75
	v_add_f32_e32 v118, v146, v162
	v_add_f32_e32 v95, v147, v164
	v_add_f32_e32 v94, v94, v165
	v_add_f32_e32 v98, v98, v166
	v_add_f32_e32 v99, v99, v167
	v_add_f32_e32 v82, v82, v170
	v_add_f32_e32 v97, v111, v172
	v_add_f32_e32 v96, v96, v173
	v_add_f32_e32 v100, v100, v174
	v_add_f32_e32 v101, v101, v175
	v_add_f32_e32 v83, v83, v171
	v_add_f32_e32 v112, v114, v200
	v_add_f32_e32 v111, v115, v201
	v_add_f32_e32 v86, v86, v202
	v_add_f32_e32 v87, v87, v203
	v_add_f32_e32 v114, v116, v204
	v_add_f32_e32 v113, v117, v205
	v_add_f32_e32 v88, v88, v206
	v_add_f32_e32 v89, v89, v207
	s_waitcnt lgkmcnt(15)
	v_add_f32_e32 v84, v84, v216
	v_add_f32_e32 v115, v102, v218
	v_add_f32_e32 v102, v103, v219
	v_add_f32_e32 v90, v90, v220
	v_add_f32_e32 v91, v91, v221
	v_add_f32_e32 v85, v85, v217
	v_add_f32_e32 v104, v104, v222
	v_add_f32_e32 v103, v105, v223
	v_add_f32_e32 v92, v92, v232
	v_add_f32_e32 v93, v93, v233
	v_add_f32_e32 v106, v106, v234
	v_add_f32_e32 v105, v107, v235
	s_waitcnt lgkmcnt(13)
	v_add_f32_e32 v70, v70, v238
	v_add_f32_e32 v71, v71, v239
	s_waitcnt lgkmcnt(12)
	v_add_f32_e32 v108, v108, v240
	v_add_f32_e32 v107, v109, v241
	s_waitcnt lgkmcnt(11)
	v_add_f32_e32 v72, v72, v242
	v_add_f32_e32 v73, v73, v243
	s_waitcnt lgkmcnt(10)
	v_add_f32_e32 v109, v144, v249
	v_add_f32_e32 v117, v148, v163
	ds_read2st64_b32 v[162:163], v48 offset0:76 offset1:77
	ds_read2st64_b32 v[164:165], v48 offset0:78 offset1:79
	ds_read2st64_b32 v[166:167], v48 offset0:80 offset1:81
	v_add_f32_e32 v119, v133, v236
	v_add_f32_e32 v120, v141, v237
	s_waitcnt lgkmcnt(12)
	v_add_f32_e32 v74, v74, v250
	v_add_f32_e32 v75, v75, v251
	v_add_f32_e32 v121, v142, v168
	v_add_f32_e32 v122, v145, v169
	ds_read2st64_b32 v[168:169], v48 offset0:82 offset1:83
	ds_read2st64_b32 v[170:171], v48 offset0:84 offset1:85
	ds_read2st64_b32 v[172:173], v48 offset0:86 offset1:87
	ds_read2st64_b32 v[174:175], v48 offset0:88 offset1:89
	ds_read2st64_b32 v[200:201], v48 offset0:90 offset1:91
	ds_read2st64_b32 v[202:203], v48 offset0:92 offset1:93
	ds_read2st64_b32 v[204:205], v48 offset0:94 offset1:95
	ds_read2st64_b32 v[206:207], v48 offset0:96 offset1:97
	ds_read2st64_b32 v[216:217], v48 offset0:98 offset1:99
	ds_read2st64_b32 v[218:219], v48 offset0:100 offset1:101
	ds_read2st64_b32 v[220:221], v48 offset0:102 offset1:103
	ds_read2st64_b32 v[222:223], v48 offset0:104 offset1:105
	ds_read2st64_b32 v[232:233], v48 offset0:106 offset1:107
	ds_read2st64_b32 v[234:235], v48 offset0:108 offset1:109
	ds_read2st64_b32 v[236:237], v48 offset0:110 offset1:111
	ds_read2st64_b32 v[238:239], v48 offset0:112 offset1:113
	ds_read2st64_b32 v[240:241], v48 offset0:114 offset1:115
	ds_read2st64_b32 v[242:243], v48 offset0:116 offset1:117
	v_add_f32_e32 v116, v143, v248
	ds_read2st64_b32 v[248:249], v48 offset0:118 offset1:119
	ds_read2st64_b32 v[250:251], v48 offset0:120 offset1:121
	s_waitcnt lgkmcnt(15)
; DI int crow(int r, int hi) { return (r & 3) + 8 * (r >> 2) + 4 * hi; }
; DI void finalize_attn(const Params& p, unsigned char* lds, f32x16 (&o)[8], float l_reg, int lane_k, int wid, bool meta, int qrow0, int hh, int di, float lambda_init, bool dry) {
;     ...
;         for (int d = 0; d < 8; ++d)
; #pragma unroll
;             for (int r = 0; r < 16; ++r) o[d][r] += X[(rg * 128 + d * 16 + r) * 64 + lane];
;         asm volatile("s_waitcnt lgkmcnt(0)" ::: "memory");
;         float* R = (float*)(lds + rg * 32768);
; #pragma unroll
;         for (int d = 0; d < 8; ++d)
; #pragma unroll
;             for (int r = 0; r < 16; ++r) R[crow(r, hi) * 256 + 32 * d + r32] = o[d][r];
	v_add_f32_e32 v76, v76, v252
	v_add_f32_e32 v77, v77, v253
	ds_read2st64_b32 v[252:253], v48 offset0:122 offset1:123
	v_add_f32_e32 v123, v130, v254
	v_add_f32_e32 v124, v131, v255
	ds_read2st64_b32 v[254:255], v48 offset0:124 offset1:125
	v_add_f32_e32 v125, v132, v226
	v_add_f32_e32 v130, v139, v227
	ds_read2st64_b32 v[226:227], v48 offset0:126 offset1:127
	v_add_f32_e32 v66, v66, v150
	v_add_f32_e32 v67, v67, v151
	v_add_f32_e32 v68, v68, v152
	v_add_f32_e32 v69, v69, v153
	v_add_f32_e32 v54, v54, v154
	v_add_f32_e32 v55, v55, v155
	v_add_f32_e32 v56, v56, v156
	v_add_f32_e32 v57, v57, v157
	v_add_f32_e32 v58, v58, v158
	v_add_f32_e32 v59, v59, v159
	v_add_f32_e32 v60, v60, v160
	v_add_f32_e32 v61, v61, v161
	v_add_f32_e32 v110, v110, v162
	v_add_f32_e32 v126, v126, v163
	v_add_f32_e32 v131, v128, v164
	v_add_f32_e32 v132, v129, v165
	v_add_f32_e32 v128, v50, v166
	v_add_f32_e32 v129, v51, v167
	v_add_f32_e32 v52, v52, v168
	v_add_f32_e32 v53, v53, v169
	v_add_f32_e32 v50, v38, v170
	v_add_f32_e32 v51, v39, v171
	v_add_f32_e32 v40, v40, v172
	v_add_f32_e32 v41, v41, v173
	v_add_f32_e32 v42, v42, v174
	v_add_f32_e32 v43, v43, v175
	v_add_f32_e32 v44, v44, v200
	v_add_f32_e32 v45, v45, v201
	s_waitcnt lgkmcnt(15)
	v_add_f32_e32 v46, v46, v202
	v_add_f32_e32 v62, v62, v203
	v_add_f32_e32 v79, v79, v204
	v_add_f32_e32 v127, v127, v205
	v_add_f32_e32 v38, v34, v206
	v_add_f32_e32 v39, v35, v207
	s_waitcnt lgkmcnt(14)
	v_add_f32_e32 v36, v36, v216
	v_add_f32_e32 v37, v37, v217
	s_waitcnt lgkmcnt(13)
	v_add_f32_e32 v34, v22, v218
	v_add_f32_e32 v35, v23, v219
	s_waitcnt lgkmcnt(12)
	v_add_f32_e32 v24, v24, v220
	v_add_f32_e32 v25, v25, v221
	s_waitcnt lgkmcnt(11)
	v_add_f32_e32 v26, v26, v222
	v_add_f32_e32 v27, v27, v223
	s_waitcnt lgkmcnt(10)
	v_add_f32_e32 v28, v28, v232
	v_add_f32_e32 v29, v29, v233
	s_waitcnt lgkmcnt(9)
	v_add_f32_e32 v30, v30, v234
	v_add_f32_e32 v133, v14, v235
	s_waitcnt lgkmcnt(8)
	v_add_f32_e32 v22, v15, v236
	v_add_f32_e32 v23, v78, v237
	s_waitcnt lgkmcnt(7)
	v_add_f32_e32 v18, v18, v238
	v_add_f32_e32 v19, v19, v239
	s_waitcnt lgkmcnt(6)
	v_add_f32_e32 v20, v20, v240
	v_add_f32_e32 v21, v21, v241
	s_waitcnt lgkmcnt(5)
	v_add_f32_e32 v14, v6, v242
	v_add_f32_e32 v15, v7, v243
	s_waitcnt lgkmcnt(4)
	v_add_f32_e32 v8, v8, v248
	v_add_f32_e32 v9, v9, v249
	s_waitcnt lgkmcnt(3)
	v_add_f32_e32 v10, v10, v250
	v_add_f32_e32 v11, v11, v251
	s_waitcnt lgkmcnt(2)
	v_add_f32_e32 v12, v12, v252
	v_add_f32_e32 v13, v13, v253
	s_waitcnt lgkmcnt(1)
	v_add_f32_e32 v6, v2, v254
	v_add_f32_e32 v7, v3, v255
	s_waitcnt lgkmcnt(0)
	v_add_f32_e32 v2, v4, v226
	v_add_f32_e32 v3, v5, v227
	v_lshlrev_b32_e32 v4, 12, v0
	v_lshlrev_b32_e32 v5, 2, v134
	v_add3_u32 v4, s6, v4, v5
	ds_write2_b32 v4, v17, v112 offset1:32
	v_add_u32_e32 v5, 0x400, v4
	v_add_u32_e32 v17, 0xc00, v4
	ds_write2_b32 v5, v16, v111 offset1:32
	v_add_u32_e32 v16, 0x800, v4
	ds_write2_b32 v17, v31, v113 offset1:32
	v_add_u32_e32 v31, 0x2000, v4
	ds_write2_b32 v16, v32, v114 offset1:32
	ds_write2_b32 v31, v47, v115 offset1:32
	v_add_u32_e32 v32, 0x2400, v4
	v_add_u32_e32 v47, 0x2c00, v4
	ds_write2_b32 v32, v33, v102 offset1:32
	v_add_u32_e32 v33, 0x2800, v4
	ds_write2_b32 v47, v49, v103 offset1:32
	v_add_u32_e32 v49, 0x4400, v4
	ds_write2_b32 v33, v63, v104 offset1:32
	v_add_u32_e32 v48, 0x4000, v4
	ds_write2_b32 v49, v64, v105 offset1:32
	v_add_u32_e32 v63, 0x4800, v4
	v_add_u32_e32 v64, 0x4c00, v4
	ds_write2_b32 v48, v65, v106 offset1:32
	ds_write2_b32 v63, v81, v108 offset1:32
	ds_write2_b32 v64, v80, v107 offset1:32
	v_add_u32_e32 v65, 0x6000, v4
	v_add_u32_e32 v78, 0x6400, v4
	v_add_u32_e32 v80, 0x6800, v4
	v_add_u32_e32 v81, 0x6c00, v4
	ds_write2_b32 v65, v95, v116 offset1:32
	ds_write2_b32 v78, v94, v109 offset1:32
	ds_write2_b32 v80, v97, v118 offset1:32
	ds_write2_b32 v81, v96, v117 offset1:32
	ds_write2_b32 v4, v98, v82 offset0:64 offset1:96
	ds_write2_b32 v5, v99, v83 offset0:64 offset1:96
	ds_write2_b32 v16, v100, v84 offset0:64 offset1:96
	ds_write2_b32 v17, v101, v85 offset0:64 offset1:96
	ds_write2_b32 v31, v86, v70 offset0:64 offset1:96
	ds_write2_b32 v32, v87, v71 offset0:64 offset1:96
	ds_write2_b32 v33, v88, v72 offset0:64 offset1:96
	ds_write2_b32 v47, v89, v73 offset0:64 offset1:96
	ds_write2_b32 v48, v90, v74 offset0:64 offset1:96
	ds_write2_b32 v49, v91, v75 offset0:64 offset1:96
	ds_write2_b32 v63, v92, v76 offset0:64 offset1:96
	ds_write2_b32 v64, v93, v77 offset0:64 offset1:96
	ds_write2_b32 v65, v119, v123 offset0:64 offset1:96
	ds_write2_b32 v78, v120, v124 offset0:64 offset1:96
	ds_write2_b32 v80, v121, v125 offset0:64 offset1:96
	ds_write2_b32 v81, v122, v130 offset0:64 offset1:96
	ds_write2_b32 v4, v66, v128 offset0:128 offset1:160
	ds_write2_b32 v5, v67, v129 offset0:128 offset1:160
	ds_write2_b32 v16, v68, v52 offset0:128 offset1:160
	ds_write2_b32 v17, v69, v53 offset0:128 offset1:160
	ds_write2_b32 v31, v54, v50 offset0:128 offset1:160
	ds_write2_b32 v32, v55, v51 offset0:128 offset1:160
	ds_write2_b32 v33, v56, v40 offset0:128 offset1:160
	ds_write2_b32 v47, v57, v41 offset0:128 offset1:160
	ds_write2_b32 v48, v58, v42 offset0:128 offset1:160
	ds_write2_b32 v49, v59, v43 offset0:128 offset1:160
	ds_write2_b32 v63, v60, v44 offset0:128 offset1:160
	ds_write2_b32 v64, v61, v45 offset0:128 offset1:160
	ds_write2_b32 v65, v110, v46 offset0:128 offset1:160
	ds_write2_b32 v78, v126, v62 offset0:128 offset1:160
	ds_write2_b32 v80, v131, v79 offset0:128 offset1:160
	ds_write2_b32 v81, v132, v127 offset0:128 offset1:160
	ds_write2_b32 v4, v38, v18 offset0:192 offset1:224
	ds_write2_b32 v5, v39, v19 offset0:192 offset1:224
	ds_write2_b32 v16, v36, v20 offset0:192 offset1:224
	ds_write2_b32 v17, v37, v21 offset0:192 offset1:224
	ds_write2_b32 v31, v34, v14 offset0:192 offset1:224
	ds_write2_b32 v32, v35, v15 offset0:192 offset1:224
	ds_write2_b32 v33, v24, v8 offset0:192 offset1:224
	ds_write2_b32 v47, v25, v9 offset0:192 offset1:224
	ds_write2_b32 v48, v26, v10 offset0:192 offset1:224
	ds_write2_b32 v49, v27, v11 offset0:192 offset1:224
	ds_write2_b32 v63, v28, v12 offset0:192 offset1:224
	ds_write2_b32 v64, v29, v13 offset0:192 offset1:224
	ds_write2_b32 v65, v30, v6 offset0:192 offset1:224
	ds_write2_b32 v78, v133, v7 offset0:192 offset1:224
	ds_write2_b32 v80, v22, v2 offset0:192 offset1:224
	ds_write2_b32 v81, v23, v3 offset0:192 offset1:224
	v_readlane_b32 s6, v245, 17
	s_waitcnt lgkmcnt(0)
; DI unsigned cvt_pk_bf16(float lo, float hi) { const f32x2_t v = {lo, hi}; const bf16v2_t b = __builtin_convertvector(v, bf16v2_t); return __builtin_bit_cast(unsigned, b); }
; DI float half_sum(float v) { v += SWZ_XOR(v, 1); v += SWZ_XOR(v, 2); v += SWZ_XOR(v, 4); v += SWZ_XOR(v, 8); v += SWZ_XOR(v, 16); return v; }
; DI void finalize_attn(const Params& p, unsigned char* lds, f32x16 (&o)[8], float l_reg, int lane_k, int wid, bool meta, int qrow0, int hh, int di, float lambda_init, bool dry) {
;     ...
;         const float og = 1.f - misc[1]; const int c8 = (lane & 31) * 8;
;         const f32x4 g0 = *(const f32x4*)(p.diff_gn + (size_t)di * 256 + c8) * og, g1 = *(const f32x4*)(p.diff_gn + (size_t)di * 256 + c8 + 4) * og;
;         bf16_t* dstb = qbuf + (size_t)(qrow0 + 32 * rg + (lane >> 5)) * 2048 + hh * 256 + c8;
;         const int nrow = dry ? 0 : (meta ? (rg == 0 ? 16 : 0) : 32);
; #pragma unroll 2
;         for (int it = 0; it < 16; ++it) {
;             const int row = 2 * it + (lane >> 5);
;             f32x4 a = *(const f32x4*)(R + row * 256 + c8), b = *(const f32x4*)(R + row * 256 + c8 + 4);
;             float ss = a[0] * a[0] + a[1] * a[1] + a[2] * a[2] + a[3] * a[3] + b[0] * b[0] + b[1] * b[1] + b[2] * b[2] + b[3] * b[3];
;             ss = half_sum(ss);
;             const float rstd = rsqrtf(ss * (1.f / 256.f) + 1e-6f);
;             a = a * rstd * g0; b = b * rstd * g1;
;             u32x4 w; w.x = cvt_pk_bf16(a[0], a[1]); w.y = cvt_pk_bf16(a[2], a[3]); w.z = cvt_pk_bf16(b[0], b[1]); w.w = cvt_pk_bf16(b[2], b[3]);
;             if (row < nrow) *(u32x4*)(dstb + (size_t)it * 4096) = w;
;         }
	v_lshlrev_b32_e32 v18, 5, v134
	s_nop 0
	v_mov_b32_e32 v2, s6
	ds_read_b32 v2, v2
	v_readlane_b32 s6, v244, 21
	v_readlane_b32 s7, v244, 22
	s_waitcnt lgkmcnt(0)
	v_sub_f32_e32 v16, 1.0, v2
	s_nop 2
	global_load_dwordx4 v[2:5], v18, s[6:7] offset:16
	global_load_dwordx4 v[6:9], v18, s[6:7]
	s_and_b64 s[6:7], s[76:77], exec
	v_readlane_b32 s7, v244, 36
	v_readlane_b32 s6, v244, 35
	s_cselect_b32 s6, s6, 32
	s_waitcnt vmcnt(1)
	v_pk_mul_f32 v[14:15], v[4:5], v[16:17] op_sel_hi:[1,0]
	s_waitcnt vmcnt(0)
	v_pk_mul_f32 v[10:11], v[8:9], v[16:17] op_sel_hi:[1,0]
	v_pk_mul_f32 v[12:13], v[6:7], v[16:17] op_sel_hi:[1,0]
	v_pk_mul_f32 v[16:17], v[2:3], v[16:17] op_sel_hi:[1,0]
	v_lshl_or_b32 v2, v0, 10, v18
	v_add_u32_e32 v20, s7, v2
	v_readlane_b32 s7, v244, 32
	s_add_i32 s7, s7, s71
	s_nop 0
	v_add_u32_e32 v2, s7, v0
	v_ashrrev_i32_e32 v3, 31, v2
	v_readlane_b32 s7, v244, 37
	v_lshlrev_b64 v[2:3], 12, v[2:3]
	s_add_u32 s8, s7, s78
	v_readlane_b32 s7, v244, 38
	v_lshl_or_b32 v2, v134, 4, v2
	s_addc_u32 s9, s7, s79
	v_lshl_add_u64 v[18:19], s[8:9], 0, v[2:3]
	s_mov_b32 s7, 0
	s_branch .LBB0_124
.LBB0_123:
	s_add_i32 s7, s7, 4
	s_mov_b64 s[8:9], 0x4000
	v_add_u32_e32 v20, 0x1000, v20
	s_cmp_lg_u32 s7, 32
	v_lshl_add_u64 v[18:19], v[18:19], 0, s[8:9]
	s_cbranch_scc0 .LBB0_77
.LBB0_124:
	ds_read_b128 v[6:9], v20
	ds_read_b128 v[150:153], v20 offset:2048
	ds_read_b128 v[2:5], v20 offset:16
	ds_read_b128 v[154:157], v20 offset:2064
	v_add_u32_e32 v21, s7, v0
	v_cmp_gt_i32_e64 s[84:85], s6, v21
	v_add_u32_e32 v21, 2, v21
	v_cmp_gt_i32_e64 s[86:87], s6, v21
	s_waitcnt lgkmcnt(2)
	v_mul_f32_e32 v22, v7, v7
	v_mul_f32_e32 v158, v151, v151
	v_fmac_f32_e32 v22, v6, v6
	v_fmac_f32_e32 v158, v150, v150
	v_fmac_f32_e32 v22, v8, v8
	v_fmac_f32_e32 v158, v152, v152
	v_fmac_f32_e32 v22, v9, v9
	v_fmac_f32_e32 v158, v153, v153
	s_waitcnt lgkmcnt(0)
	v_fmac_f32_e32 v22, v2, v2
	v_fmac_f32_e32 v158, v154, v154
	v_fmac_f32_e32 v22, v3, v3
	v_fmac_f32_e32 v158, v155, v155
	v_fmac_f32_e32 v22, v4, v4
	v_fmac_f32_e32 v158, v156, v156
	v_fmac_f32_e32 v22, v5, v5
	v_fmac_f32_e32 v158, v157, v157
	s_nop 0
	v_add_f32_dpp v22, v22, v22 quad_perm:[1,0,3,2] row_mask:0xf bank_mask:0xf
	v_add_f32_dpp v158, v158, v158 quad_perm:[1,0,3,2] row_mask:0xf bank_mask:0xf
	s_nop 0
	v_add_f32_dpp v22, v22, v22 quad_perm:[2,3,0,1] row_mask:0xf bank_mask:0xf
	v_add_f32_dpp v158, v158, v158 quad_perm:[2,3,0,1] row_mask:0xf bank_mask:0xf
	s_nop 0
	v_add_f32_dpp v22, v22, v22 row_half_mirror row_mask:0xf bank_mask:0xf
	v_add_f32_dpp v158, v158, v158 row_half_mirror row_mask:0xf bank_mask:0xf
	s_nop 0
	v_add_f32_dpp v22, v22, v22 row_mirror row_mask:0xf bank_mask:0xf
	v_add_f32_dpp v158, v158, v158 row_mirror row_mask:0xf bank_mask:0xf
	ds_swizzle_b32 v23, v22 offset:swizzle(SWAP,16)
	ds_swizzle_b32 v159, v158 offset:swizzle(SWAP,16)
	v_add_co_u32_e32 v160, vcc, 0xffffe000, v18
	s_nop 1
	v_addc_co_u32_e32 v161, vcc, -1, v19, vcc
	s_waitcnt lgkmcnt(0)
	v_add_f32_e32 v22, v22, v23
	v_add_f32_e32 v158, v158, v159
	v_fmamk_f32 v22, v22, 0x3b800000, v185
	v_fmamk_f32 v158, v158, 0x3b800000, v185
	v_mul_f32_e32 v23, 0x4b800000, v22
	v_mul_f32_e32 v159, 0x4b800000, v158
	v_cmp_gt_f32_e32 vcc, s25, v22
	v_cmp_gt_f32_e64 s[88:89], s25, v158
	s_nop 1
	v_cndmask_b32_e32 v22, v22, v23, vcc
	v_cndmask_b32_e64 v158, v158, v159, s[88:89]
	v_rsq_f32_e32 v22, v22
	v_rsq_f32_e32 v158, v158
	s_nop 0
	v_mul_f32_e32 v23, 0x45800000, v22
	v_mul_f32_e32 v159, 0x45800000, v158
	v_cndmask_b32_e32 v22, v22, v23, vcc
	v_cndmask_b32_e64 v158, v158, v159, s[88:89]
	v_pk_mul_f32 v[6:7], v[6:7], v[22:23] op_sel_hi:[1,0]
	v_pk_mul_f32 v[150:151], v[150:151], v[158:159] op_sel_hi:[1,0]
	v_pk_mul_f32 v[8:9], v[8:9], v[22:23] op_sel_hi:[1,0]
	v_pk_mul_f32 v[152:153], v[152:153], v[158:159] op_sel_hi:[1,0]
	v_pk_mul_f32 v[2:3], v[2:3], v[22:23] op_sel_hi:[1,0]
	v_pk_mul_f32 v[154:155], v[154:155], v[158:159] op_sel_hi:[1,0]
	v_pk_mul_f32 v[4:5], v[4:5], v[22:23] op_sel_hi:[1,0]
	v_pk_mul_f32 v[156:157], v[156:157], v[158:159] op_sel_hi:[1,0]
	v_pk_mul_f32 v[8:9], v[10:11], v[8:9]
	v_pk_mul_f32 v[152:153], v[10:11], v[152:153]
	v_pk_mul_f32 v[6:7], v[12:13], v[6:7]
	v_pk_mul_f32 v[150:151], v[12:13], v[150:151]
	v_pk_mul_f32 v[2:3], v[16:17], v[2:3]
	v_pk_mul_f32 v[154:155], v[16:17], v[154:155]
	v_pk_mul_f32 v[4:5], v[14:15], v[4:5]
	v_pk_mul_f32 v[156:157], v[14:15], v[156:157]
	v_cvt_pk_bf16_f32 v6, v6, v7
	v_cvt_pk_bf16_f32 v150, v150, v151
	v_cvt_pk_bf16_f32 v7, v8, v9
	v_cvt_pk_bf16_f32 v151, v152, v153
	v_cvt_pk_bf16_f32 v8, v2, v3
	v_cvt_pk_bf16_f32 v152, v154, v155
	v_cvt_pk_bf16_f32 v9, v4, v5
	v_cvt_pk_bf16_f32 v153, v156, v157
	s_and_saveexec_b64 s[8:9], s[84:85]
	global_store_dwordx4 v[160:161], v[6:9], off
	s_mov_b64 exec, s[8:9]
	s_and_saveexec_b64 s[8:9], s[86:87]
	global_store_dwordx4 v[18:19], v[150:153], off
	s_mov_b64 exec, s[8:9]
	s_branch .LBB0_123
